# ssd_out store part: norm-weight rows loaded once (8 loads), one wait, 16 stores without intermediate waits
# baseline (speedup 1.0000x reference)
.LBB0_1284:
	s_or_b64 exec, exec, s[4:5]
	s_waitcnt lgkmcnt(0)
	s_barrier
	s_load_dwordx2 s[2:3], s[20:21], 0x80
	ds_read_b128 v[18:21], v85
	ds_read_b128 v[22:25], v85 offset:16
	s_waitcnt lgkmcnt(0)
	v_mov_b32_e32 v26, v18
	v_mov_b32_e32 v27, v22
	v_mov_b32_e32 v22, v19
	v_pk_add_f32 v[18:19], v[26:27], v[22:23]
	v_mov_b32_e32 v22, v20
	v_mov_b32_e32 v23, v24
	v_mov_b32_e32 v24, v21
	v_pk_add_f32 v[20:21], v[22:23], v[24:25]
	s_add_u32 s2, s2, s12
	v_pk_add_f32 v[18:19], v[18:19], v[20:21]
	s_addc_u32 s3, s3, s13
	v_add_f32_e32 v18, v18, v19
	v_fmamk_f32 v18, v18, 0x3b000000, v177
	v_cmp_gt_f32_e32 vcc, s53, v18
	v_mul_f32_e32 v19, 0x4f800000, v18
	s_add_u32 s2, s2, s10
	v_cndmask_b32_e32 v18, v18, v19, vcc
	v_sqrt_f32_e32 v19, v18
	s_addc_u32 s3, s3, s11
	v_lshl_add_u64 v[16:17], v[90:91], 2, s[2:3]
	global_load_dwordx4 v[126:129], v[16:17], off
	global_load_dwordx4 v[130:133], v[16:17], off offset:32
	global_load_dwordx4 v[134:137], v[16:17], off offset:64
	global_load_dwordx4 v[138:141], v[16:17], off offset:96
	global_load_dwordx4 v[142:145], v[16:17], off offset:128
	global_load_dwordx4 v[148:151], v[16:17], off offset:160
	global_load_dwordx4 v[152:155], v[16:17], off offset:192
	global_load_dwordx4 v[158:161], v[16:17], off offset:224
	v_add_u32_e32 v20, -1, v19
	v_fma_f32 v21, -v20, v19, v18
	v_cmp_ge_f32_e64 s[4:5], 0, v21
	v_add_u32_e32 v21, 1, v19
	s_nop 0
	v_cndmask_b32_e64 v20, v19, v20, s[4:5]
	v_fma_f32 v19, -v21, v19, v18
	v_cmp_lt_f32_e64 s[4:5], 0, v19
	s_nop 1
	v_cndmask_b32_e64 v19, v20, v21, s[4:5]
	v_mul_f32_e32 v20, 0x37800000, v19
	v_cndmask_b32_e32 v19, v19, v20, vcc
	v_cmp_class_f32_e32 vcc, v18, v234
	s_nop 1
	v_cndmask_b32_e32 v18, v19, v18, vcc
	v_div_scale_f32 v19, s[2:3], v18, v18, 1.0
	v_rcp_f32_e32 v20, v19
	s_nop 0
	v_fma_f32 v21, -v19, v20, 1.0
	v_fmac_f32_e32 v20, v21, v20
	v_div_scale_f32 v21, vcc, 1.0, v18, 1.0
	v_mul_f32_e32 v22, v21, v20
	v_fma_f32 v23, -v19, v22, v21
	v_fmac_f32_e32 v22, v23, v20
	v_fma_f32 v19, -v19, v22, v21
	v_div_fmas_f32 v19, v19, v20, v22
	v_div_fixup_f32 v18, v19, v18, 1.0
	v_pk_mul_f32 v[24:25], v[116:117], v[18:19] op_sel_hi:[1,0]
	v_pk_mul_f32 v[26:27], v[112:113], v[18:19] op_sel_hi:[1,0]
	s_waitcnt vmcnt(0)
	v_pk_mul_f32 v[20:21], v[126:127], v[24:25]
	v_pk_mul_f32 v[24:25], v[118:119], v[18:19] op_sel_hi:[1,0]
	v_cvt_pk_bf16_f32 v20, v20, v21
	v_pk_mul_f32 v[22:23], v[128:129], v[24:25]
	v_lshl_add_u64 v[24:25], v[100:101], 0, v[110:111]
	v_cvt_pk_bf16_f32 v21, v22, v23
	global_store_dwordx2 v[24:25], v[20:21], off
	s_nop 0
	v_pk_mul_f32 v[20:21], v[130:131], v[26:27]
	v_pk_mul_f32 v[26:27], v[114:115], v[18:19] op_sel_hi:[1,0]
	v_cvt_pk_bf16_f32 v20, v20, v21
	v_pk_mul_f32 v[22:23], v[132:133], v[26:27]
	v_pk_mul_f32 v[26:27], v[80:81], v[18:19] op_sel_hi:[1,0]
	v_cvt_pk_bf16_f32 v21, v22, v23
	global_store_dwordx2 v[24:25], v[20:21], off offset:16
	s_nop 0
	v_pk_mul_f32 v[20:21], v[134:135], v[26:27]
	v_pk_mul_f32 v[26:27], v[82:83], v[18:19] op_sel_hi:[1,0]
	v_cvt_pk_bf16_f32 v20, v20, v21
	v_pk_mul_f32 v[22:23], v[136:137], v[26:27]
	v_pk_mul_f32 v[26:27], v[120:121], v[18:19] op_sel_hi:[1,0]
	v_cvt_pk_bf16_f32 v21, v22, v23
	global_store_dwordx2 v[24:25], v[20:21], off offset:32
	s_nop 0
	v_pk_mul_f32 v[20:21], v[138:139], v[26:27]
	v_pk_mul_f32 v[26:27], v[122:123], v[18:19] op_sel_hi:[1,0]
	v_cvt_pk_bf16_f32 v20, v20, v21
	v_pk_mul_f32 v[22:23], v[140:141], v[26:27]
	v_pk_mul_f32 v[26:27], v[64:65], v[18:19] op_sel_hi:[1,0]
	v_cvt_pk_bf16_f32 v21, v22, v23
	global_store_dwordx2 v[24:25], v[20:21], off offset:48
	s_nop 0
	v_pk_mul_f32 v[20:21], v[26:27], v[142:143]
	v_pk_mul_f32 v[26:27], v[66:67], v[18:19] op_sel_hi:[1,0]
	v_cvt_pk_bf16_f32 v20, v20, v21
	v_pk_mul_f32 v[22:23], v[26:27], v[144:145]
	v_pk_mul_f32 v[26:27], v[56:57], v[18:19] op_sel_hi:[1,0]
	v_cvt_pk_bf16_f32 v21, v22, v23
	global_store_dwordx2 v[24:25], v[20:21], off offset:64
	s_nop 0
	v_pk_mul_f32 v[20:21], v[26:27], v[148:149]
	v_pk_mul_f32 v[26:27], v[58:59], v[18:19] op_sel_hi:[1,0]
	v_cvt_pk_bf16_f32 v20, v20, v21
	v_pk_mul_f32 v[22:23], v[26:27], v[150:151]
	v_pk_mul_f32 v[26:27], v[48:49], v[18:19] op_sel_hi:[1,0]
	v_cvt_pk_bf16_f32 v21, v22, v23
	global_store_dwordx2 v[24:25], v[20:21], off offset:80
	s_nop 0
	v_pk_mul_f32 v[20:21], v[26:27], v[152:153]
	v_pk_mul_f32 v[26:27], v[52:53], v[18:19] op_sel_hi:[1,0]
	v_cvt_pk_bf16_f32 v20, v20, v21
	v_pk_mul_f32 v[22:23], v[26:27], v[154:155]
	v_pk_mul_f32 v[26:27], v[60:61], v[18:19] op_sel_hi:[1,0]
	v_cvt_pk_bf16_f32 v21, v22, v23
	global_store_dwordx2 v[24:25], v[20:21], off offset:96
	s_nop 0
	v_pk_mul_f32 v[18:19], v[78:79], v[18:19] op_sel_hi:[1,0]
	v_pk_mul_f32 v[20:21], v[26:27], v[158:159]
	v_pk_mul_f32 v[18:19], v[18:19], v[160:161]
	v_cvt_pk_bf16_f32 v20, v20, v21
	v_cvt_pk_bf16_f32 v21, v18, v19
	global_store_dwordx2 v[24:25], v[20:21], off offset:112
	s_nop 0
	ds_read_b128 v[18:21], v93
	ds_read_b128 v[22:25], v93 offset:16
	s_waitcnt lgkmcnt(1)
	v_mov_b32_e32 v26, v18
	s_waitcnt lgkmcnt(0)
	v_mov_b32_e32 v27, v22
	v_mov_b32_e32 v22, v19
	v_pk_add_f32 v[18:19], v[26:27], v[22:23]
	v_mov_b32_e32 v22, v20
	v_mov_b32_e32 v23, v24
	v_mov_b32_e32 v24, v21
	v_pk_add_f32 v[20:21], v[22:23], v[24:25]
	s_nop 0
	v_pk_add_f32 v[18:19], v[18:19], v[20:21]
	s_nop 0
	v_add_f32_e32 v18, v18, v19
	v_fmamk_f32 v18, v18, 0x3b000000, v177
	v_cmp_gt_f32_e32 vcc, s53, v18
	v_mul_f32_e32 v19, 0x4f800000, v18
	s_nop 0
	v_cndmask_b32_e32 v18, v18, v19, vcc
	v_sqrt_f32_e32 v19, v18
	s_nop 0
	v_add_u32_e32 v20, -1, v19
	v_fma_f32 v21, -v20, v19, v18
	v_cmp_ge_f32_e64 s[4:5], 0, v21
	v_add_u32_e32 v21, 1, v19
	s_nop 0
	v_cndmask_b32_e64 v20, v19, v20, s[4:5]
	v_fma_f32 v19, -v21, v19, v18
	v_cmp_lt_f32_e64 s[4:5], 0, v19
	s_nop 1
	v_cndmask_b32_e64 v19, v20, v21, s[4:5]
	v_mul_f32_e32 v20, 0x37800000, v19
	v_cndmask_b32_e32 v19, v19, v20, vcc
	v_cmp_class_f32_e32 vcc, v18, v234
	s_mov_b64 s[4:5], 0
	s_nop 0
	v_cndmask_b32_e32 v18, v19, v18, vcc
	v_div_scale_f32 v19, s[2:3], v18, v18, 1.0
	v_rcp_f32_e32 v20, v19
	s_nop 0
	v_fma_f32 v21, -v19, v20, 1.0
	v_fmac_f32_e32 v20, v21, v20
	v_div_scale_f32 v21, vcc, 1.0, v18, 1.0
	v_mul_f32_e32 v22, v21, v20
	v_fma_f32 v23, -v19, v22, v21
	v_fmac_f32_e32 v22, v23, v20
	v_fma_f32 v19, -v19, v22, v21
	v_div_fmas_f32 v19, v19, v20, v22
	v_div_fixup_f32 v18, v19, v18, 1.0
	v_pk_mul_f32 v[24:25], v[70:71], v[18:19] op_sel_hi:[1,0]
	v_pk_mul_f32 v[26:27], v[54:55], v[18:19] op_sel_hi:[1,0]
	v_pk_mul_f32 v[0:1], v[0:1], v[18:19] op_sel_hi:[1,0]
	v_pk_mul_f32 v[2:3], v[2:3], v[18:19] op_sel_hi:[1,0]
	v_pk_mul_f32 v[4:5], v[4:5], v[18:19] op_sel_hi:[1,0]
	v_pk_mul_f32 v[20:21], v[126:127], v[24:25]
	v_pk_mul_f32 v[24:25], v[74:75], v[18:19] op_sel_hi:[1,0]
	v_cvt_pk_bf16_f32 v20, v20, v21
	v_pk_mul_f32 v[22:23], v[128:129], v[24:25]
	v_lshl_add_u64 v[24:25], v[100:101], 0, v[50:51]
	v_cvt_pk_bf16_f32 v21, v22, v23
	global_store_dwordx2 v[24:25], v[20:21], off
	s_nop 0
	v_pk_mul_f32 v[20:21], v[130:131], v[26:27]
	v_pk_mul_f32 v[26:27], v[62:63], v[18:19] op_sel_hi:[1,0]
	v_cvt_pk_bf16_f32 v20, v20, v21
	v_pk_mul_f32 v[22:23], v[132:133], v[26:27]
	v_pk_mul_f32 v[26:27], v[68:69], v[18:19] op_sel_hi:[1,0]
	v_cvt_pk_bf16_f32 v21, v22, v23
	global_store_dwordx2 v[24:25], v[20:21], off offset:16
	s_nop 0
	v_pk_mul_f32 v[20:21], v[134:135], v[26:27]
	v_pk_mul_f32 v[26:27], v[72:73], v[18:19] op_sel_hi:[1,0]
	v_cvt_pk_bf16_f32 v20, v20, v21
	v_pk_mul_f32 v[22:23], v[136:137], v[26:27]
	v_pk_mul_f32 v[26:27], v[76:77], v[18:19] op_sel_hi:[1,0]
	v_cvt_pk_bf16_f32 v21, v22, v23
	global_store_dwordx2 v[24:25], v[20:21], off offset:32
	s_nop 0
	v_pk_mul_f32 v[20:21], v[138:139], v[26:27]
	v_pk_mul_f32 v[26:27], v[124:125], v[18:19] op_sel_hi:[1,0]
	v_cvt_pk_bf16_f32 v20, v20, v21
	v_pk_mul_f32 v[22:23], v[140:141], v[26:27]
	s_nop 0
	v_cvt_pk_bf16_f32 v21, v22, v23
	global_store_dwordx2 v[24:25], v[20:21], off offset:48
	s_nop 0
	v_pk_mul_f32 v[0:1], v[0:1], v[142:143]
	v_pk_mul_f32 v[2:3], v[2:3], v[144:145]
	v_cvt_pk_bf16_f32 v0, v0, v1
	v_cvt_pk_bf16_f32 v1, v2, v3
	global_store_dwordx2 v[24:25], v[0:1], off offset:64
	s_nop 0
	v_pk_mul_f32 v[0:1], v[4:5], v[148:149]
	v_pk_mul_f32 v[4:5], v[6:7], v[18:19] op_sel_hi:[1,0]
	v_cvt_pk_bf16_f32 v0, v0, v1
	v_pk_mul_f32 v[2:3], v[4:5], v[150:151]
	v_pk_mul_f32 v[4:5], v[8:9], v[18:19] op_sel_hi:[1,0]
	v_cvt_pk_bf16_f32 v1, v2, v3
	global_store_dwordx2 v[24:25], v[0:1], off offset:80
	s_nop 0
	v_pk_mul_f32 v[0:1], v[4:5], v[152:153]
	v_pk_mul_f32 v[4:5], v[10:11], v[18:19] op_sel_hi:[1,0]
	v_cvt_pk_bf16_f32 v0, v0, v1
	v_pk_mul_f32 v[2:3], v[4:5], v[154:155]
	v_pk_mul_f32 v[4:5], v[12:13], v[18:19] op_sel_hi:[1,0]
	v_cvt_pk_bf16_f32 v1, v2, v3
	global_store_dwordx2 v[24:25], v[0:1], off offset:96
	s_nop 0
	v_pk_mul_f32 v[0:1], v[4:5], v[158:159]
	v_pk_mul_f32 v[4:5], v[14:15], v[18:19] op_sel_hi:[1,0]
	v_cvt_pk_bf16_f32 v0, v0, v1
	v_pk_mul_f32 v[2:3], v[4:5], v[160:161]
	s_nop 0
	v_cvt_pk_bf16_f32 v1, v2, v3
	global_store_dwordx2 v[24:25], v[0:1], off offset:112
	s_nop 0
	s_barrier
